# sample_gemm_resid K=2816: 11 dependent load groups -> ring of 5 groups in flight with counted waits
# speedup vs baseline: 1.0015x; 1.0015x over previous
.LBB0_392:
	s_and_b32 s4, s9, 62
	s_or_b32 s5, s4, s6
	s_ashr_i32 s4, s10, 1
	s_and_b32 s4, s4, -16
	s_addk_i32 s4, 0x4000
	v_or_b32_e32 v0, s4, v147
	s_movk_i32 s11, 0x1600
	v_lshl_or_b32 v25, s5, 4, v147
	v_mad_i64_i32 v[2:3], s[12:13], v0, s11, v[16:17]
	v_mul_u32_u24_e32 v0, 0xb00, v25
	v_lshlrev_b32_e32 v144, 1, v0
	v_lshl_add_u64 v[0:1], v[18:19], 0, v[144:145]
	global_load_dwordx4 v[12:15], v[2:3], off
	global_load_dwordx4 v[26:29], v[0:1], off
	global_load_dwordx4 v[30:33], v[2:3], off offset:64
	global_load_dwordx4 v[34:37], v[0:1], off offset:64
	global_load_dwordx4 v[134:137], v[2:3], off offset:128
	global_load_dwordx4 v[138:141], v[0:1], off offset:128
	global_load_dwordx4 v[162:165], v[2:3], off offset:192
	global_load_dwordx4 v[166:169], v[0:1], off offset:192
	global_load_dwordx4 v[172:175], v[2:3], off offset:256
	global_load_dwordx4 v[176:179], v[0:1], off offset:256
	global_load_dwordx4 v[180:183], v[2:3], off offset:320
	global_load_dwordx4 v[184:187], v[0:1], off offset:320
	global_load_dwordx4 v[212:215], v[2:3], off offset:384
	global_load_dwordx4 v[216:219], v[0:1], off offset:384
	global_load_dwordx4 v[220:223], v[2:3], off offset:448
	global_load_dwordx4 v[224:227], v[0:1], off offset:448
	global_load_dwordx4 v[228:231], v[2:3], off offset:512
	global_load_dwordx4 v[232:235], v[0:1], off offset:512
	global_load_dwordx4 v[236:239], v[2:3], off offset:576
	global_load_dwordx4 v[242:245], v[0:1], off offset:576
	s_andn2_b64 vcc, exec, s[0:1]
	s_waitcnt vmcnt(18)
	v_mfma_f32_16x16x32_bf16 v[4:7], v[12:15], v[26:29], 0
	s_waitcnt vmcnt(16)
	v_mfma_f32_16x16x32_bf16 v[8:11], v[30:33], v[34:37], 0
	global_load_dwordx4 v[12:15], v[2:3], off offset:640
	global_load_dwordx4 v[26:29], v[0:1], off offset:640
	global_load_dwordx4 v[30:33], v[2:3], off offset:704
	global_load_dwordx4 v[34:37], v[0:1], off offset:704
	s_waitcnt vmcnt(18)
	v_mfma_f32_16x16x32_bf16 v[4:7], v[134:137], v[138:141], v[4:7]
	s_waitcnt vmcnt(16)
	v_mfma_f32_16x16x32_bf16 v[8:11], v[162:165], v[166:169], v[8:11]
	global_load_dwordx4 v[134:137], v[2:3], off offset:768
	global_load_dwordx4 v[138:141], v[0:1], off offset:768
	global_load_dwordx4 v[162:165], v[2:3], off offset:832
	global_load_dwordx4 v[166:169], v[0:1], off offset:832
	s_waitcnt vmcnt(18)
	v_mfma_f32_16x16x32_bf16 v[4:7], v[172:175], v[176:179], v[4:7]
	s_waitcnt vmcnt(16)
	v_mfma_f32_16x16x32_bf16 v[8:11], v[180:183], v[184:187], v[8:11]
	global_load_dwordx4 v[172:175], v[2:3], off offset:896
	global_load_dwordx4 v[176:179], v[0:1], off offset:896
	global_load_dwordx4 v[180:183], v[2:3], off offset:960
	global_load_dwordx4 v[184:187], v[0:1], off offset:960
	s_waitcnt vmcnt(18)
	v_mfma_f32_16x16x32_bf16 v[4:7], v[212:215], v[216:219], v[4:7]
	s_waitcnt vmcnt(16)
	v_mfma_f32_16x16x32_bf16 v[8:11], v[220:223], v[224:227], v[8:11]
	global_load_dwordx4 v[212:215], v[2:3], off offset:1024
	global_load_dwordx4 v[216:219], v[0:1], off offset:1024
	global_load_dwordx4 v[220:223], v[2:3], off offset:1088
	global_load_dwordx4 v[224:227], v[0:1], off offset:1088
	s_waitcnt vmcnt(18)
	v_mfma_f32_16x16x32_bf16 v[4:7], v[228:231], v[232:235], v[4:7]
	s_waitcnt vmcnt(16)
	v_mfma_f32_16x16x32_bf16 v[8:11], v[236:239], v[242:245], v[8:11]
	global_load_dwordx4 v[228:231], v[2:3], off offset:1152
	global_load_dwordx4 v[232:235], v[0:1], off offset:1152
	global_load_dwordx4 v[236:239], v[2:3], off offset:1216
	global_load_dwordx4 v[242:245], v[0:1], off offset:1216
	s_waitcnt vmcnt(18)
	v_mfma_f32_16x16x32_bf16 v[4:7], v[12:15], v[26:29], v[4:7]
	s_waitcnt vmcnt(16)
	v_mfma_f32_16x16x32_bf16 v[8:11], v[30:33], v[34:37], v[8:11]
	global_load_dwordx4 v[12:15], v[2:3], off offset:1280
	global_load_dwordx4 v[26:29], v[0:1], off offset:1280
	global_load_dwordx4 v[30:33], v[2:3], off offset:1344
	global_load_dwordx4 v[34:37], v[0:1], off offset:1344
	s_waitcnt vmcnt(18)
	v_mfma_f32_16x16x32_bf16 v[4:7], v[134:137], v[138:141], v[4:7]
	s_waitcnt vmcnt(16)
	v_mfma_f32_16x16x32_bf16 v[8:11], v[162:165], v[166:169], v[8:11]
	s_waitcnt vmcnt(14)
	v_mfma_f32_16x16x32_bf16 v[4:7], v[172:175], v[176:179], v[4:7]
	s_waitcnt vmcnt(12)
	v_mfma_f32_16x16x32_bf16 v[8:11], v[180:183], v[184:187], v[8:11]
	s_waitcnt vmcnt(10)
	v_mfma_f32_16x16x32_bf16 v[4:7], v[212:215], v[216:219], v[4:7]
	s_waitcnt vmcnt(8)
	v_mfma_f32_16x16x32_bf16 v[8:11], v[220:223], v[224:227], v[8:11]
	s_waitcnt vmcnt(6)
	v_mfma_f32_16x16x32_bf16 v[4:7], v[228:231], v[232:235], v[4:7]
	s_waitcnt vmcnt(4)
	v_mfma_f32_16x16x32_bf16 v[8:11], v[236:239], v[242:245], v[8:11]
	s_barrier
	s_waitcnt vmcnt(2)
	v_mfma_f32_16x16x32_bf16 v[4:7], v[12:15], v[26:29], v[4:7]
	s_waitcnt vmcnt(0)
	v_mfma_f32_16x16x32_bf16 v[0:3], v[30:33], v[34:37], v[8:11]
	s_nop 7
	v_pk_add_f32 v[2:3], v[6:7], v[2:3]
	v_pk_add_f32 v[0:1], v[4:5], v[0:1]
	ds_write_b128 v22, v[0:3]
	s_waitcnt lgkmcnt(0)
	s_barrier
	s_cbranch_vccnz .LBB0_391
	v_or_b32_e32 v20, s4, v24
	v_ashrrev_i32_e32 v21, 31, v20
	v_lshlrev_b64 v[26:27], 12, v[20:21]
	v_lshlrev_b32_e32 v21, 2, v25
	v_readlane_b32 s12, v250, 4
	v_or_b32_e32 v26, v26, v21
	v_readlane_b32 s13, v250, 5
	ds_read_b128 v[12:15], v23
	ds_read_b128 v[4:7], v23 offset:2048
	ds_read_b128 v[0:3], v23 offset:4096
	ds_read_b128 v[8:11], v23 offset:6144
	v_lshl_add_u64 v[28:29], s[12:13], 0, v[26:27]
	v_lshl_add_u64 v[26:27], s[66:67], 0, v[26:27]
	global_load_dword v26, v[26:27], off
	v_or_b32_e32 v242, 1, v20
	v_ashrrev_i32_e32 v243, 31, v242
	v_lshlrev_b64 v[242:243], 12, v[242:243]
	v_or_b32_e32 v242, v242, v21
	v_lshl_add_u64 v[242:243], s[66:67], 0, v[242:243]
	global_load_dword v246, v[242:243], off
	v_or_b32_e32 v242, 2, v20
	v_ashrrev_i32_e32 v243, 31, v242
	v_lshlrev_b64 v[242:243], 12, v[242:243]
	v_or_b32_e32 v242, v242, v21
	v_lshl_add_u64 v[242:243], s[66:67], 0, v[242:243]
	global_load_dword v247, v[242:243], off
	v_or_b32_e32 v242, 3, v20
	v_ashrrev_i32_e32 v243, 31, v242
	v_lshlrev_b64 v[242:243], 12, v[242:243]
	v_or_b32_e32 v242, v242, v21
	v_lshl_add_u64 v[242:243], s[66:67], 0, v[242:243]
	global_load_dword v248, v[242:243], off
	s_waitcnt lgkmcnt(3)
	v_mov_b32_e32 v30, v12
	s_waitcnt lgkmcnt(1)
	v_mov_b32_e32 v31, v0
	v_mov_b32_e32 v32, v4
	s_waitcnt lgkmcnt(0)
	v_mov_b32_e32 v33, v8
	v_pk_add_f32 v[30:31], v[30:31], v[32:33]
	v_mov_b32_e32 v8, v5
	v_pk_add_f32 v[30:31], v[30:31], v[30:31] op_sel_hi:[0,1]
	v_mov_b32_e32 v27, v31
	v_mul_f32_e32 v0, 0.5, v31
	s_mov_b32 s4, s53
	s_mov_b32 s5, s52
	s_nop 0
	s_waitcnt vmcnt(3)
	v_pk_fma_f32 v[26:27], v[26:27], s[52:53], v[0:1] op_sel_hi:[1,1,0]
	global_store_dword v[28:29], v26, off sc1
	v_or_b32_e32 v26, 1, v20
	v_ashrrev_i32_e32 v27, 31, v26
	v_lshlrev_b64 v[26:27], 12, v[26:27]
	v_or_b32_e32 v26, v26, v21
	v_lshl_add_u64 v[28:29], s[12:13], 0, v[26:27]
	v_lshl_add_u64 v[26:27], s[66:67], 0, v[26:27]
	s_nop 0
	v_mov_b32_e32 v0, v13
	v_pk_add_f32 v[0:1], v[0:1], v[8:9]
	v_mov_b32_e32 v8, v6
	v_pk_add_f32 v[0:1], v[0:1], v[0:1] op_sel:[0,1] op_sel_hi:[1,0]
	v_mov_b32_e32 v9, v10
	v_mov_b32_e32 v10, v7
	s_nop 0
	s_waitcnt vmcnt(3)
	v_mov_b32_e32 v1, v246
	v_mul_f32_e32 v4, 0x3fd744fd, v246
	v_pk_fma_f32 v[0:1], v[0:1], s[4:5], v[4:5] op_sel_hi:[1,1,0]
	global_store_dword v[28:29], v0, off sc1
	v_or_b32_e32 v0, 2, v20
	v_ashrrev_i32_e32 v1, 31, v0
	v_lshlrev_b64 v[0:1], 12, v[0:1]
	v_or_b32_e32 v0, v0, v21
	v_lshl_add_u64 v[4:5], s[12:13], 0, v[0:1]
	v_lshl_add_u64 v[0:1], s[66:67], 0, v[0:1]
	s_nop 0
	v_mov_b32_e32 v0, v14
	v_mov_b32_e32 v1, v2
	v_pk_add_f32 v[0:1], v[0:1], v[8:9]
	s_nop 0
	s_waitcnt vmcnt(3)
	v_mul_f32_e32 v2, 0x3fd744fd, v247
	v_pk_add_f32 v[0:1], v[0:1], v[0:1] op_sel:[0,1] op_sel_hi:[1,0]
	s_nop 0
	v_mov_b32_e32 v1, v247
	v_pk_fma_f32 v[0:1], v[0:1], s[4:5], v[2:3] op_sel_hi:[1,1,0]
	global_store_dword v[4:5], v0, off sc1
	v_or_b32_e32 v0, 3, v20
	v_ashrrev_i32_e32 v1, 31, v0
	v_lshlrev_b64 v[0:1], 12, v[0:1]
	v_or_b32_e32 v0, v0, v21
	v_lshl_add_u64 v[4:5], s[12:13], 0, v[0:1]
	v_lshl_add_u64 v[0:1], s[66:67], 0, v[0:1]
	s_nop 0
	v_mov_b32_e32 v2, v15
	v_pk_add_f32 v[0:1], v[2:3], v[10:11]
	s_nop 0
	s_waitcnt vmcnt(3)
	v_mul_f32_e32 v2, 0x3fd744fd, v248
	v_pk_add_f32 v[0:1], v[0:1], v[0:1] op_sel:[0,1] op_sel_hi:[1,0]
	s_nop 0
	v_mov_b32_e32 v1, v248
	v_pk_fma_f32 v[0:1], v[0:1], s[4:5], v[2:3] op_sel_hi:[1,1,0]
	global_store_dword v[4:5], v0, off sc1
	s_branch .LBB0_391
